# v33 + residual-phase sample tile (on half the workgroups, critical path): 8 LDS reduction reads issued together, residual loads hoisted to tile start
# speedup vs baseline: 1.0151x; 1.0151x over previous
; template <int MODE>
; __device__ __forceinline__ void sgemm_phase(LAS unsigned char* lds, const SgArgs g, int ntiles, int bid, int G) {
;     ...
;     for (int t = bid; t < ntiles; t += G) {
;         const int ct = t >> 3, rt = t & 7;
;         const int brow0 = MODE == 0 ? 256 * (ct >> 2) + 32 * (ct & 3) : 64 * ct, brow1 = MODE == 0 ? brow0 + 128 : brow0 + 32;
;         const bf16_t* ap = g.A + (size_t)(MP + rt * 32 + r32) * g.lda + wave * kw + hi * 8;
;         const bf16_t* bp0 = g.Bt + (size_t)(brow0 + r32) * g.ldb + wave * kw + hi * 8;
;         const bf16_t* bp1 = g.Bt + (size_t)(brow1 + r32) * g.ldb + wave * kw + hi * 8;
;         f32x16 c0 = {}, c1 = {};
;     ...
;             const size_t off = (size_t)grow * D + 64 * ct + 2 * q;
;             const unsigned xa = *(const unsigned*)(g.XB + off), xb = *(const unsigned*)(g.XB + off + 32);
.LBB0_660:
	s_lshl_b32 s3, s21, 5
	s_and_b32 s5, s3, 0xe0
	s_bitset1_b32 s5, 15
	v_or_b32_e32 v0, s5, v144
	s_ashr_i32 s4, s21, 3
	v_mul_u32_u24_e32 v0, s46, v0
	s_lshl_b32 s8, s4, 6
	v_lshlrev_b32_e32 v0, 1, v0
	v_lshl_add_u64 v[138:139], v[132:133], 0, v[0:1]
	v_or_b32_e32 v0, s8, v144
	v_mad_i64_i32 v[140:141], s[10:11], s20, v0, v[134:135]
	v_or_b32_e32 v0, s8, v147
	v_mov_b32_e32 v14, v1
	v_mov_b32_e32 v15, v1
	v_mad_i64_i32 v[142:143], s[10:11], s20, v0, v[134:135]
	v_mov_b32_e32 v0, v1
	v_mov_b32_e32 v2, v1
	v_mov_b32_e32 v3, v1
	v_mov_b32_e32 v4, v1
	v_mov_b32_e32 v5, v1
	v_mov_b32_e32 v6, v1
	v_mov_b32_e32 v7, v1
	v_mov_b32_e32 v8, v1
	v_mov_b32_e32 v9, v1
	v_mov_b32_e32 v10, v1
	v_mov_b32_e32 v11, v1
	v_mov_b32_e32 v12, v1
	v_mov_b32_e32 v13, v1
	v_mov_b64_e32 v[30:31], v[14:15]
	v_mov_b64_e32 v[46:47], v[14:15]
	v_mov_b64_e32 v[28:29], v[12:13]
	v_mov_b64_e32 v[26:27], v[10:11]
	v_mov_b64_e32 v[24:25], v[8:9]
	v_mov_b64_e32 v[22:23], v[6:7]
	v_mov_b64_e32 v[20:21], v[4:5]
	v_mov_b64_e32 v[18:19], v[2:3]
	v_mov_b64_e32 v[16:17], v[0:1]
	v_mov_b64_e32 v[44:45], v[12:13]
	v_mov_b64_e32 v[42:43], v[10:11]
	v_mov_b64_e32 v[40:41], v[8:9]
	v_mov_b64_e32 v[38:39], v[6:7]
	v_mov_b64_e32 v[36:37], v[4:5]
	v_mov_b64_e32 v[34:35], v[2:3]
	v_mov_b64_e32 v[32:33], v[0:1]
	s_mov_b32 s9, 0
	v_add_u32_e32 v150, s5, v146
	v_ashrrev_i32_e32 v151, 31, v150
	v_lshlrev_b64 v[152:153], 11, v[150:151]
	v_lshl_add_u64 v[152:153], s[14:15], 0, v[152:153]
	v_lshl_add_u64 v[152:153], s[8:9], 1, v[152:153]
	v_mov_b32_e32 v154, v136
	v_mov_b32_e32 v155, v1
	v_lshl_add_u64 v[152:153], v[152:153], 0, v[154:155]
	global_load_dword v156, v[152:153], off
	global_load_dword v157, v[152:153], off offset:64
	s_branch .LBB0_662

; #define LAS __attribute__((address_space(3)))
; template <int MODE>
; __device__ __forceinline__ void sgemm_phase(LAS unsigned char* lds, const SgArgs g, int ntiles, int bid, int G) {
;     ...
;         LAS float* red = (LAS float*)lds + wave * 2048;
; #pragma unroll
;         for (int r = 0; r < 16; ++r) { const int row = (r & 3) + 8 * (r >> 2) + 4 * hi; red[row * 64 + r32] = c0[r]; red[row * 64 + 32 + r32] = c1[r]; }
;         __syncthreads();
;         const int row = tid >> 4, q = tid & 15; float v0 = 0.f, v1 = 0.f, v2 = 0.f, v3 = 0.f;
; #pragma unroll
;         for (int w = 0; w < 8; ++w) { const LAS float* p = (const LAS float*)lds + w * 2048 + row * 64 + 2 * q; const f32x2 lo = *(const LAS f32x2*)p, hi2 = *(const LAS f32x2*)(p + 32); v0 += lo.x; v1 += lo.y; v2 += hi2.x; v3 += hi2.y; }
;         const int grow = MP + rt * 32 + row;
;         if (MODE == 0) {
;             const float rs = row_rstd(g.ssq_in, grow); const float g0 = v0 * rs, g1 = v1 * rs, u0 = v2 * rs, u1 = v3 * rs;
;             const float a0 = g0 * __builtin_amdgcn_rcpf(1.0f + __builtin_amdgcn_exp2f(-1.4426950408889634f * g0)) * u0, a1 = g1 * __builtin_amdgcn_rcpf(1.0f + __builtin_amdgcn_exp2f(-1.4426950408889634f * g1)) * u1;
;             *(unsigned*)(g.O + (size_t)grow * g.ldc + 128 * (ct >> 2) + 32 * (ct & 3) + 2 * q) = cvt_pk_bf16(a0, a1);
;         } else if (MODE == 1) {
;             const float rs = row_rstd(g.ssq_in, grow); bf16_t* op = g.O + (size_t)grow * g.ldc + 64 * ct + 2 * q;
;             *(unsigned*)op = cvt_pk_bf16(v0 * rs, v1 * rs); *(unsigned*)(op + 32) = cvt_pk_bf16(v2 * rs, v3 * rs);
;         } else {
;             const size_t off = (size_t)grow * D + 64 * ct + 2 * q;
;             const unsigned xa = *(const unsigned*)(g.XB + off), xb = *(const unsigned*)(g.XB + off + 32);
;             const float n0 = bf_lo(xa) + g.scale * v0, n1 = bf_hi(xa) + g.scale * v1, n2 = bf_lo(xb) + g.scale * v2, n3 = bf_hi(xb) + g.scale * v3;
;             *(unsigned*)(g.XB + off) = cvt_pk_bf16(n0, n1); *(unsigned*)(g.XB + off + 32) = cvt_pk_bf16(n2, n3);
;             float ss = (n0 * n0 + n1 * n1) + (n2 * n2 + n3 * n3);
;             ss += __shfl_xor(ss, 1); ss += __shfl_xor(ss, 2); ss += __shfl_xor(ss, 4); ss += __shfl_xor(ss, 8);
;             if (q == 0) g.ssq_out[(size_t)grow * 16 + ct] = ss;
;         }
.LBB0_690:
	v_add_u32_e32 v0, 0x800, v145
	s_nop 3
	ds_write2_b32 v145, v16, v32 offset1:32
	ds_write2_b32 v145, v17, v33 offset0:64 offset1:96
	ds_write2_b32 v145, v18, v34 offset0:128 offset1:160
	ds_write2_b32 v145, v19, v35 offset0:192 offset1:224
	ds_write2_b32 v0, v20, v36 offset1:32
	ds_write2_b32 v0, v21, v37 offset0:64 offset1:96
	ds_write2_b32 v0, v22, v38 offset0:128 offset1:160
	ds_write2_b32 v0, v23, v39 offset0:192 offset1:224
	v_add_u32_e32 v0, 0x1000, v145
	ds_write2_b32 v0, v24, v40 offset1:32
	ds_write2_b32 v0, v25, v41 offset0:64 offset1:96
	ds_write2_b32 v0, v26, v42 offset0:128 offset1:160
	ds_write2_b32 v0, v27, v43 offset0:192 offset1:224
	v_add_u32_e32 v0, 0x1800, v145
	ds_write2_b32 v0, v28, v44 offset1:32
	ds_write2_b32 v0, v29, v45 offset0:64 offset1:96
	ds_write2_b32 v0, v30, v46 offset0:128 offset1:160
	ds_write2_b32 v0, v31, v47 offset0:192 offset1:224
	s_waitcnt lgkmcnt(0)
	s_barrier
	ds_read2_b64 v[164:167], v148 offset1:16
	v_add_u32_e32 v2, 0x2000, v148
	ds_read2_b64 v[168:171], v2 offset1:16
	v_add_u32_e32 v2, 0x4000, v148
	ds_read2_b64 v[172:175], v2 offset1:16
	v_add_u32_e32 v2, 0x6000, v148
	ds_read2_b64 v[176:179], v2 offset1:16
	v_add_u32_e32 v2, 0x8000, v148
	ds_read2_b64 v[180:183], v2 offset1:16
	v_add_u32_e32 v2, 0xa000, v148
	ds_read2_b64 v[190:193], v2 offset1:16
	v_add_u32_e32 v2, 0xc000, v148
	ds_read2_b64 v[194:197], v2 offset1:16
	v_add_u32_e32 v2, 0xe000, v148
	ds_read2_b64 v[198:201], v2 offset1:16
	s_ashr_i32 s9, s8, 31
	v_mov_b32_e32 v137, v1
	s_waitcnt lgkmcnt(0)
	v_add_f32_e32 v0, 0, v164
	v_add_f32_e32 v6, 0, v165
	v_add_f32_e32 v7, 0, v166
	v_add_f32_e32 v8, 0, v167
	v_add_f32_e32 v0, v0, v168
	v_add_f32_e32 v6, v6, v169
	v_add_f32_e32 v7, v7, v170
	v_add_f32_e32 v8, v8, v171
	v_add_f32_e32 v0, v0, v172
	v_add_f32_e32 v6, v6, v173
	v_add_f32_e32 v7, v7, v174
	v_add_f32_e32 v8, v8, v175
	v_add_f32_e32 v0, v0, v176
	v_add_f32_e32 v6, v6, v177
	v_add_f32_e32 v7, v7, v178
	v_add_f32_e32 v8, v8, v179
	v_add_f32_e32 v0, v0, v180
	v_add_f32_e32 v6, v6, v181
	v_add_f32_e32 v7, v7, v182
	v_add_f32_e32 v8, v8, v183
	v_add_f32_e32 v0, v0, v190
	v_add_f32_e32 v6, v6, v191
	v_add_f32_e32 v7, v7, v192
	v_add_f32_e32 v8, v8, v193
	v_add_f32_e32 v0, v0, v194
	v_add_f32_e32 v6, v6, v195
	v_add_f32_e32 v7, v7, v196
	v_add_f32_e32 v8, v8, v197
	v_add_f32_e32 v0, v0, v198
	v_add_f32_e32 v6, v6, v199
	v_add_f32_e32 v7, v7, v200
	v_add_f32_e32 v8, v8, v201
	v_add_u32_e32 v2, s5, v146
	v_ashrrev_i32_e32 v3, 31, v2
	v_lshlrev_b64 v[4:5], 11, v[2:3]
	v_lshl_add_u64 v[4:5], s[14:15], 0, v[4:5]
	v_lshl_add_u64 v[4:5], s[8:9], 1, v[4:5]
	v_lshl_add_u64 v[4:5], v[4:5], 0, v[136:137]
	v_mov_b32_e32 v9, v156
	v_mov_b32_e32 v10, v157
	s_waitcnt vmcnt(0) lgkmcnt(0)
	v_lshlrev_b32_e32 v11, 16, v9
	v_fmac_f32_e32 v11, s2, v0
	v_and_b32_e32 v0, 0xffff0000, v9
	v_fmac_f32_e32 v0, s2, v6
	v_lshlrev_b32_e32 v6, 16, v10
	v_fmac_f32_e32 v6, s2, v7
	v_and_b32_e32 v7, 0xffff0000, v10
	v_fmac_f32_e32 v7, s2, v8
	v_cvt_pk_bf16_f32 v8, v11, v0
	flat_store_dword v[4:5], v8
	v_cvt_pk_bf16_f32 v8, v6, v7
	flat_store_dword v[4:5], v8 offset:64
	v_mul_f32_e32 v0, v0, v0
	v_mul_f32_e32 v4, v7, v7
	v_fmac_f32_e32 v0, v11, v11
	v_fmac_f32_e32 v4, v6, v6
	v_and_b32_e32 v5, 64, v185
	v_add_f32_e32 v0, v0, v4
	v_xor_b32_e32 v4, 1, v185
	v_add_u32_e32 v5, 64, v5
	v_cmp_lt_i32_e32 vcc, v4, v5
	s_nop 1
	v_cndmask_b32_e32 v4, v185, v4, vcc
	v_lshlrev_b32_e32 v4, 2, v4
	ds_bpermute_b32 v4, v4, v0
	s_waitcnt lgkmcnt(0)
	v_add_f32_e32 v0, v0, v4
	v_xor_b32_e32 v4, 2, v185
	v_cmp_lt_i32_e32 vcc, v4, v5
	s_nop 1
	v_cndmask_b32_e32 v4, v185, v4, vcc
	v_lshlrev_b32_e32 v4, 2, v4
	ds_bpermute_b32 v4, v4, v0
	s_waitcnt lgkmcnt(0)
	v_add_f32_e32 v0, v0, v4
	v_xor_b32_e32 v4, 4, v185
	v_cmp_lt_i32_e32 vcc, v4, v5
	s_nop 1
	v_cndmask_b32_e32 v4, v185, v4, vcc
	v_lshlrev_b32_e32 v4, 2, v4
	ds_bpermute_b32 v4, v4, v0
	s_waitcnt lgkmcnt(0)
	v_add_f32_e32 v0, v0, v4
	v_xor_b32_e32 v4, 8, v185
	v_cmp_lt_i32_e32 vcc, v4, v5
	s_nop 1
	v_cndmask_b32_e32 v4, v185, v4, vcc
	v_lshlrev_b32_e32 v4, 2, v4
	ds_bpermute_b32 v4, v4, v0
	s_and_saveexec_b64 s[8:9], s[0:1]
	s_cbranch_execz .LBB0_659
	v_lshlrev_b64 v[2:3], 6, v[2:3]
	v_lshl_add_u64 v[2:3], s[12:13], 0, v[2:3]
	s_ashr_i32 s5, s4, 31
	s_waitcnt lgkmcnt(0)
	v_add_f32_e32 v0, v0, v4
	v_lshl_add_u64 v[2:3], s[4:5], 2, v[2:3]
	flat_store_dword v[2:3], v0
	s_branch .LBB0_659
